# group-A skewed loop: s_setprio 1 for the wave group in the QK+softmax-finish phase, 0 in the P.V phase
# speedup vs baseline: 1.0005x; 1.0005x over previous
.LskewA_in:
.LBB0_236:
	s_mov_b32 s40, s4
	s_setprio 1
	v_mov_b32_e32 v68, 0
	s_waitcnt lgkmcnt(0)
	v_sub_u32_e32 v66, v254, v201
	v_cmp_lt_i32_e32 vcc, s87, v66
	v_cmp_gt_i32_e64 s[12:13], s84, v66
	s_and_saveexec_b64 s[4:5], s[12:13]
	v_mov_b32_e32 v66, s86
	ds_read_b32 v68, v66
	s_or_b64 exec, exec, s[4:5]
	global_load_dword v253, v[184:185], off
	s_lshl_b32 s45, s39, 14
	s_add_i32 s45, s45, s44
	s_add_i32 s48, s45, 0xc000
	s_mov_b32 m0, s48
	s_mov_b64 exec, s[8:9]
	s_add_i32 s48, s48, 0x2000
	global_load_lds_dwordx4 v[116:117], off
	s_mov_b32 m0, s48
	s_nop 0
	global_load_lds_dwordx4 v[118:119], off
	s_mov_b64 exec, -1
	v_lshl_add_u64 v[116:117], v[116:117], 0, s[62:63]
	v_lshl_add_u64 v[118:119], v[118:119], 0, s[62:63]
	s_lshl_b32 s43, s33, 14
	v_add_u32_e32 v66, s43, v221
	v_add_u32_e32 v67, v66, v210
	ds_read_b128 v[226:229], v67 offset:49152
	ds_read_b128 v[238:241], v67 offset:57344
	s_waitcnt lgkmcnt(2)
	v_mov_b32_e32 v69, v68
	v_mov_b32_e32 v70, v68
	v_mov_b32_e32 v71, v68
	v_mov_b32_e32 v72, v68
	v_mov_b32_e32 v73, v68
	v_mov_b32_e32 v74, v68
	v_mov_b32_e32 v75, v68
	v_mov_b32_e32 v76, v68
	v_mov_b32_e32 v77, v68
	v_mov_b32_e32 v78, v68
	v_mov_b32_e32 v79, v68
	v_mov_b32_e32 v80, v68
	v_mov_b32_e32 v81, v68
	v_mov_b32_e32 v82, v68
	v_mov_b32_e32 v83, v68
	v_add_u32_e32 v67, v66, v212
	v_exp_f32_e32 v219, v136
	s_waitcnt lgkmcnt(1)
	v_mfma_f32_32x32x16_bf16 v[84:99], v[226:229], v[100:103], v[68:83]
	v_exp_f32_e32 v130, v130
	v_exp_f32_e32 v131, v131
	v_exp_f32_e32 v128, v128
	v_exp_f32_e32 v129, v129
	v_exp_f32_e32 v126, v126
	v_exp_f32_e32 v127, v127
	v_exp_f32_e32 v124, v124
	s_waitcnt lgkmcnt(0)
	v_mfma_f32_32x32x16_bf16 v[68:83], v[238:241], v[100:103], v[68:83]
	ds_read_b128 v[226:229], v67 offset:49152
	ds_read_b128 v[238:241], v67 offset:57344
	v_add_u32_e32 v67, v66, v213
	v_add_u32_e32 v66, v66, v214
	v_exp_f32_e32 v125, v125
	s_waitcnt lgkmcnt(0)
	v_mfma_f32_32x32x16_bf16 v[68:83], v[238:241], v[104:107], v[68:83]
	v_mfma_f32_32x32x16_bf16 v[84:99], v[226:229], v[104:107], v[84:99]
	ds_read_b128 v[226:229], v67 offset:49152
	ds_read_b128 v[238:241], v67 offset:57344
	v_exp_f32_e32 v67, v139
	s_waitcnt lgkmcnt(0)
	v_mfma_f32_32x32x16_bf16 v[68:83], v[238:241], v[108:111], v[68:83]
	v_mfma_f32_32x32x16_bf16 v[84:99], v[226:229], v[108:111], v[84:99]
	ds_read_b128 v[226:229], v66 offset:49152
	ds_read_b128 v[238:241], v66 offset:57344
	v_exp_f32_e32 v66, v138
	s_waitcnt lgkmcnt(0)
	v_mfma_f32_32x32x16_bf16 v[68:83], v[238:241], v[112:115], v[68:83]
	v_exp_f32_e32 v238, v132
	v_add_f32_e32 v132, 0, v230
	v_add_f32_e32 v132, v234, v132
	v_add_f32_e32 v132, v231, v132
	v_add_f32_e32 v132, v235, v132
	v_add_f32_e32 v132, v232, v132
	v_add_f32_e32 v132, v236, v132
	v_add_f32_e32 v132, v233, v132
	v_add_f32_e32 v132, v237, v132
	v_add_f32_e32 v132, v140, v132
	v_add_f32_e32 v132, v143, v132
	v_add_f32_e32 v132, v141, v132
	v_add_f32_e32 v132, v144, v132
	v_add_f32_e32 v132, v142, v132
	v_add_f32_e32 v132, v146, v132
	v_add_f32_e32 v132, v145, v132
	v_mfma_f32_32x32x16_bf16 v[84:99], v[226:229], v[112:115], v[84:99]
	v_exp_f32_e32 v227, v137
	v_add_f32_e32 v132, v147, v132
	v_exp_f32_e32 v228, v134
	v_add_f32_e32 v132, v66, v132
	v_exp_f32_e32 v229, v135
	v_add_f32_e32 v132, v67, v132
	v_add_f32_e32 v132, v219, v132
	v_exp_f32_e32 v239, v133
	v_add_f32_e32 v132, v227, v132
	v_add_f32_e32 v132, v228, v132
	v_add_f32_e32 v132, v229, v132
	v_add_f32_e32 v132, v238, v132
	v_add_f32_e32 v132, v239, v132
	v_add_f32_e32 v132, v130, v132
	v_add_f32_e32 v132, v131, v132
	v_add_f32_e32 v132, v128, v132
	v_add_f32_e32 v132, v129, v132
	v_add_f32_e32 v132, v126, v132
	v_add_f32_e32 v132, v127, v132
	v_add_f32_e32 v132, v124, v132
	v_add_f32_e32 v225, v125, v132
	ds_bpermute_b32 v226, v187, v225
	v_cvt_pk_bf16_f32 v132, v230, v234
	v_cvt_pk_bf16_f32 v133, v231, v235
	v_cvt_pk_bf16_f32 v134, v232, v236
	v_cvt_pk_bf16_f32 v135, v233, v237
	v_cvt_pk_bf16_f32 v136, v140, v143
	v_cvt_pk_bf16_f32 v137, v141, v144
	v_cvt_pk_bf16_f32 v138, v142, v146
	v_cvt_pk_bf16_f32 v139, v145, v147
	v_cvt_pk_bf16_f32 v140, v66, v67
	v_cvt_pk_bf16_f32 v141, v219, v227
	v_cvt_pk_bf16_f32 v142, v228, v229
	v_cvt_pk_bf16_f32 v143, v238, v239
	v_cvt_pk_bf16_f32 v144, v130, v131
	v_cvt_pk_bf16_f32 v145, v128, v129
	v_cvt_pk_bf16_f32 v146, v126, v127
	v_cvt_pk_bf16_f32 v147, v124, v125
	s_nop 0
	v_permlane32_swap_b32_e32 v132, v134
	v_permlane32_swap_b32_e32 v133, v135
	v_permlane32_swap_b32_e32 v136, v138
	v_permlane32_swap_b32_e32 v137, v139
	v_permlane32_swap_b32_e32 v140, v142
	v_permlane32_swap_b32_e32 v141, v143
	v_permlane32_swap_b32_e32 v144, v146
	v_permlane32_swap_b32_e32 v145, v147
	s_waitcnt vmcnt(2)
	s_barrier
	s_setprio 0
	s_lshl_b32 s45, s40, 14
	s_add_i32 s45, s45, s44
	s_mov_b32 m0, s45
	s_add_i32 s45, s45, 0x2000
	global_load_lds_dwordx4 v[120:121], off
	s_mov_b32 m0, s45
	v_lshl_add_u64 v[120:121], v[120:121], 0, s[62:63]
	global_load_lds_dwordx4 v[122:123], off
	v_lshl_add_u64 v[122:123], v[122:123], 0, s[62:63]
	s_lshl_b32 s42, s39, 14
	v_add_u32_e32 v219, s42, v188
	ds_read_b64_tr_b16 v[228:229], v219 offset:0
	ds_read_b64_tr_b16 v[230:231], v219 offset:0x800
	ds_read_b64_tr_b16 v[232:233], v219 offset:0x1000
	ds_read_b64_tr_b16 v[234:235], v219 offset:0x1800
	ds_read_b64_tr_b16 v[236:237], v219 offset:0x2000
	ds_read_b64_tr_b16 v[238:239], v219 offset:0x2800
	ds_read_b64_tr_b16 v[240:241], v219 offset:0x3000
	ds_read_b64_tr_b16 v[242:243], v219 offset:0x3800
	s_waitcnt lgkmcnt(0)
	s_nop 0
	v_mfma_f32_32x32x16_bf16 v[50:65], v[132:135], v[228:231], v[50:65]
	ds_read_b64_tr_b16 v[228:229], v219 offset:0x200
	ds_read_b64_tr_b16 v[230:231], v219 offset:0xa00
	v_mfma_f32_32x32x16_bf16 v[50:65], v[136:139], v[232:235], v[50:65]
	ds_read_b64_tr_b16 v[232:233], v219 offset:0x1200
	ds_read_b64_tr_b16 v[234:235], v219 offset:0x1a00
	v_mfma_f32_32x32x16_bf16 v[50:65], v[140:143], v[236:239], v[50:65]
	ds_read_b64_tr_b16 v[236:237], v219 offset:0x2200
	ds_read_b64_tr_b16 v[238:239], v219 offset:0x2a00
	v_mfma_f32_32x32x16_bf16 v[50:65], v[144:147], v[240:243], v[50:65]
	ds_read_b64_tr_b16 v[240:241], v219 offset:0x3200
	ds_read_b64_tr_b16 v[242:243], v219 offset:0x3a00
	s_waitcnt lgkmcnt(0)
	v_mfma_f32_32x32x16_bf16 v[34:49], v[132:135], v[228:231], v[34:49]
	ds_read_b64_tr_b16 v[228:229], v219 offset:0x400
	ds_read_b64_tr_b16 v[230:231], v219 offset:0xc00
	v_mfma_f32_32x32x16_bf16 v[34:49], v[136:139], v[232:235], v[34:49]
	ds_read_b64_tr_b16 v[232:233], v219 offset:0x1400
	ds_read_b64_tr_b16 v[234:235], v219 offset:0x1c00
	v_mfma_f32_32x32x16_bf16 v[34:49], v[140:143], v[236:239], v[34:49]
	ds_read_b64_tr_b16 v[236:237], v219 offset:0x2400
	ds_read_b64_tr_b16 v[238:239], v219 offset:0x2c00
	v_mfma_f32_32x32x16_bf16 v[34:49], v[144:147], v[240:243], v[34:49]
	ds_read_b64_tr_b16 v[240:241], v219 offset:0x3400
	ds_read_b64_tr_b16 v[242:243], v219 offset:0x3c00
	s_waitcnt lgkmcnt(0)
	v_mfma_f32_32x32x16_bf16 v[18:33], v[132:135], v[228:231], v[18:33]
	ds_read_b64_tr_b16 v[228:229], v219 offset:0x600
	ds_read_b64_tr_b16 v[230:231], v219 offset:0xe00
	v_mfma_f32_32x32x16_bf16 v[18:33], v[136:139], v[232:235], v[18:33]
	ds_read_b64_tr_b16 v[232:233], v219 offset:0x1600
	ds_read_b64_tr_b16 v[234:235], v219 offset:0x1e00
	v_mfma_f32_32x32x16_bf16 v[18:33], v[140:143], v[236:239], v[18:33]
	ds_read_b64_tr_b16 v[236:237], v219 offset:0x2600
	ds_read_b64_tr_b16 v[238:239], v219 offset:0x2e00
	v_mfma_f32_32x32x16_bf16 v[18:33], v[144:147], v[240:243], v[18:33]
	ds_read_b64_tr_b16 v[240:241], v219 offset:0x3600
	ds_read_b64_tr_b16 v[242:243], v219 offset:0x3e00
	s_waitcnt lgkmcnt(0)
	v_mfma_f32_32x32x16_bf16 v[2:17], v[132:135], v[228:231], v[2:17]
	v_mfma_f32_32x32x16_bf16 v[2:17], v[136:139], v[232:235], v[2:17]
	v_mfma_f32_32x32x16_bf16 v[2:17], v[140:143], v[236:239], v[2:17]
	v_mfma_f32_32x32x16_bf16 v[2:17], v[144:147], v[240:243], v[2:17]
	s_and_saveexec_b64 s[4:5], vcc
	s_cbranch_execz .LBB0_242
	flat_load_dwordx4 v[132:135], v[182:183] offset:256
	flat_load_dwordx4 v[136:139], v[182:183] offset:384
	flat_load_dwordx4 v[140:143], v[182:183] offset:288
	flat_load_dwordx4 v[144:147], v[182:183] offset:416
	flat_load_dwordx4 v[228:231], v[182:183] offset:320
	flat_load_dwordx4 v[232:235], v[182:183] offset:448
	flat_load_dwordx4 v[236:239], v[182:183] offset:352
	flat_load_dwordx4 v[240:243], v[182:183] offset:480
	s_waitcnt vmcnt(0) lgkmcnt(0)
	v_sub_u32_e32 v66, v132, v167
	v_sub_u32_e32 v67, v136, v167
	v_sub_u32_e32 v132, v133, v167
	v_sub_u32_e32 v133, v137, v167
	v_sub_u32_e32 v134, v134, v167
	v_sub_u32_e32 v136, v138, v167
	v_sub_u32_e32 v135, v135, v167
	v_sub_u32_e32 v137, v139, v167
	v_sub_u32_e32 v138, v140, v167
	v_sub_u32_e32 v139, v144, v167
	v_sub_u32_e32 v140, v141, v167
	v_sub_u32_e32 v141, v145, v167
	v_sub_u32_e32 v142, v142, v167
	v_sub_u32_e32 v144, v146, v167
	v_sub_u32_e32 v143, v143, v167
	v_sub_u32_e32 v145, v147, v167
	v_sub_u32_e32 v146, v228, v167
	v_sub_u32_e32 v228, v233, v167
	v_med3_i32 v66, v66, s87, v197
	v_med3_i32 v67, v67, s87, v197
	v_med3_i32 v132, v132, s87, v197
	v_med3_i32 v133, v133, s87, v197
	v_med3_i32 v134, v134, s87, v197
	v_med3_i32 v136, v136, s87, v197
	v_med3_i32 v135, v135, s87, v197
	v_med3_i32 v137, v137, s87, v197
	v_med3_i32 v138, v138, s87, v197
	v_med3_i32 v139, v139, s87, v197
	v_med3_i32 v141, v141, s87, v197
	v_med3_i32 v142, v142, s87, v197
	v_med3_i32 v144, v144, s87, v197
	v_med3_i32 v143, v143, s87, v197
	v_med3_i32 v145, v145, s87, v197
	v_sub_u32_e32 v227, v229, v167
	v_med3_i32 v140, v140, s87, v197
	v_med3_i32 v228, v228, s87, v197
	v_lshl_add_u32 v66, v66, 2, s86
	v_lshl_add_u32 v67, v67, 2, s86
	v_lshl_add_u32 v229, v132, 2, s86
	v_lshl_add_u32 v133, v133, 2, s86
	v_lshl_add_u32 v134, v134, 2, s86
	v_lshl_add_u32 v136, v136, 2, s86
	v_lshl_add_u32 v135, v135, 2, s86
	v_lshl_add_u32 v137, v137, 2, s86
	v_lshl_add_u32 v138, v138, 2, s86
	v_lshl_add_u32 v139, v139, 2, s86
	v_lshl_add_u32 v141, v141, 2, s86
	v_lshl_add_u32 v142, v142, 2, s86
	v_lshl_add_u32 v144, v144, 2, s86
	v_lshl_add_u32 v143, v143, 2, s86
	v_lshl_add_u32 v145, v145, 2, s86
	v_sub_u32_e32 v147, v232, v167
	v_lshl_add_u32 v232, v140, 2, s86
	v_lshl_add_u32 v233, v228, 2, s86
	ds_read_b32 v66, v66 offset:1220
	ds_read_b32 v132, v67 offset:1220
	ds_read_b32 v67, v229 offset:1220
	ds_read_b32 v133, v133 offset:1220
	ds_read_b32 v134, v134 offset:1220
	ds_read_b32 v136, v136 offset:1220
	ds_read_b32 v135, v135 offset:1220
	ds_read_b32 v137, v137 offset:1220
	ds_read_b32 v138, v138 offset:1220
	ds_read_b32 v140, v139 offset:1220
	ds_read_b32 v139, v232 offset:1220
	ds_read_b32 v141, v141 offset:1220
	ds_read_b32 v142, v142 offset:1220
	ds_read_b32 v144, v144 offset:1220
	ds_read_b32 v143, v143 offset:1220
	ds_read_b32 v145, v145 offset:1220
	v_sub_u32_e32 v228, v230, v167
	v_sub_u32_e32 v229, v234, v167
	v_med3_i32 v228, v228, s87, v197
	v_med3_i32 v229, v229, s87, v197
	v_lshl_add_u32 v230, v228, 2, s86
	v_lshl_add_u32 v232, v229, 2, s86
	v_sub_u32_e32 v228, v231, v167
	v_sub_u32_e32 v229, v235, v167
	v_med3_i32 v146, v146, s87, v197
	v_med3_i32 v147, v147, s87, v197
	v_med3_i32 v228, v228, s87, v197
	v_med3_i32 v229, v229, s87, v197
	v_med3_i32 v227, v227, s87, v197
	v_lshl_add_u32 v146, v146, 2, s86
	v_lshl_add_u32 v147, v147, 2, s86
	v_lshl_add_u32 v231, v228, 2, s86
	v_lshl_add_u32 v234, v229, 2, s86
	v_lshl_add_u32 v227, v227, 2, s86
	ds_read_b32 v146, v146 offset:1220
	ds_read_b32 v228, v147 offset:1220
	ds_read_b32 v147, v227 offset:1220
	ds_read_b32 v229, v233 offset:1220
	ds_read_b32 v230, v230 offset:1220
	ds_read_b32 v232, v232 offset:1220
	ds_read_b32 v231, v231 offset:1220
	ds_read_b32 v233, v234 offset:1220
	v_sub_u32_e32 v234, v240, v167
	v_med3_i32 v234, v234, s87, v197
	v_sub_u32_e32 v227, v236, v167
	v_lshl_add_u32 v235, v234, 2, s86
	v_sub_u32_e32 v234, v237, v167
	v_sub_u32_e32 v236, v241, v167
	v_med3_i32 v234, v234, s87, v197
	v_med3_i32 v236, v236, s87, v197
	v_lshl_add_u32 v237, v234, 2, s86
	v_lshl_add_u32 v244, v236, 2, s86
	v_sub_u32_e32 v234, v238, v167
	v_sub_u32_e32 v236, v242, v167
	v_med3_i32 v234, v234, s87, v197
	v_med3_i32 v236, v236, s87, v197
	v_lshl_add_u32 v238, v234, 2, s86
	v_lshl_add_u32 v240, v236, 2, s86
	v_sub_u32_e32 v234, v239, v167
	v_sub_u32_e32 v236, v243, v167
	v_med3_i32 v227, v227, s87, v197
	v_med3_i32 v234, v234, s87, v197
	v_med3_i32 v236, v236, s87, v197
	v_lshl_add_u32 v227, v227, 2, s86
	v_lshl_add_u32 v239, v234, 2, s86
	v_lshl_add_u32 v241, v236, 2, s86
	ds_read_b32 v234, v227 offset:1220
	ds_read_b32 v236, v235 offset:1220
	ds_read_b32 v238, v238 offset:1220
	ds_read_b32 v239, v239 offset:1220
	ds_read_b32 v235, v237 offset:1220
	ds_read_b32 v241, v241 offset:1220
	ds_read_b32 v240, v240 offset:1220
	ds_read_b32 v237, v244 offset:1220
	s_waitcnt lgkmcnt(4)
	v_pk_add_f32 v[98:99], v[98:99], v[238:239]
	s_waitcnt lgkmcnt(3)
	v_pk_add_f32 v[96:97], v[96:97], v[234:235]
	v_pk_add_f32 v[94:95], v[94:95], v[230:231]
	v_pk_add_f32 v[92:93], v[92:93], v[146:147]
	v_pk_add_f32 v[90:91], v[90:91], v[142:143]
	v_pk_add_f32 v[88:89], v[88:89], v[138:139]
	v_pk_add_f32 v[86:87], v[86:87], v[134:135]
	v_pk_add_f32 v[84:85], v[84:85], v[66:67]
	s_waitcnt lgkmcnt(1)
	v_pk_add_f32 v[82:83], v[82:83], v[240:241]
	s_waitcnt lgkmcnt(0)
	v_pk_add_f32 v[80:81], v[80:81], v[236:237]
	v_pk_add_f32 v[78:79], v[78:79], v[232:233]
	v_pk_add_f32 v[76:77], v[76:77], v[228:229]
	v_pk_add_f32 v[74:75], v[74:75], v[144:145]
	v_pk_add_f32 v[72:73], v[72:73], v[140:141]
	v_pk_add_f32 v[70:71], v[70:71], v[136:137]
	v_pk_add_f32 v[68:69], v[68:69], v[132:133]

.LBB0_248:
	s_waitcnt lgkmcnt(0)
	s_barrier
	s_setprio 1
	s_waitcnt lgkmcnt(0)
	v_sub_u32_e32 v66, v253, v201
	v_cmp_lt_i32_e32 vcc, s87, v66
	v_cmp_gt_i32_e64 s[14:15], s84, v66
	v_mov_b32_e32 v66, 0
	s_and_saveexec_b64 s[4:5], s[14:15]
	v_mov_b32_e32 v66, s86
	ds_read_b32 v66, v66
	s_or_b64 exec, exec, s[4:5]
	global_load_dword v254, v[184:185], off offset:4
	s_lshl_b32 s45, s33, 14
	s_add_i32 s45, s45, s44
	s_add_i32 s48, s45, 0xc000
	s_mov_b32 m0, s48
	s_mov_b64 exec, s[8:9]
	s_add_i32 s48, s48, 0x2000
	global_load_lds_dwordx4 v[116:117], off
	s_mov_b32 m0, s48
	s_nop 0
	global_load_lds_dwordx4 v[118:119], off
	s_mov_b64 exec, -1
	v_lshl_add_u64 v[116:117], v[116:117], 0, s[62:63]
	v_lshl_add_u64 v[118:119], v[118:119], 0, s[62:63]
	v_cndmask_b32_e64 v224, v67, v224, s[12:13]
	v_mul_f32_e32 v132, 0xbe38aa3b, v224
	v_fmamk_f32 v138, v99, 0x3e38aa3b, v132
	v_exp_f32_e32 v139, v138
	v_add_u32_e32 v138, s41, v221
	v_fmamk_f32 v242, v82, 0x3e38aa3b, v132
	v_add_u32_e32 v82, v138, v210
	ds_read_b128 v[140:143], v82 offset:49152
	ds_read_b128 v[144:147], v82 offset:57344
	v_fmamk_f32 v67, v84, 0x3e38aa3b, v132
	v_fmamk_f32 v84, v85, 0x3e38aa3b, v132
	v_fmamk_f32 v85, v86, 0x3e38aa3b, v132
	v_fmamk_f32 v86, v87, 0x3e38aa3b, v132
	v_fmamk_f32 v87, v88, 0x3e38aa3b, v132
	v_fmamk_f32 v88, v89, 0x3e38aa3b, v132
	v_fmamk_f32 v89, v90, 0x3e38aa3b, v132
	v_fmamk_f32 v90, v91, 0x3e38aa3b, v132
	v_fmamk_f32 v91, v92, 0x3e38aa3b, v132
	v_fmamk_f32 v92, v93, 0x3e38aa3b, v132
	v_fmamk_f32 v93, v94, 0x3e38aa3b, v132
	v_fmamk_f32 v94, v95, 0x3e38aa3b, v132
	v_fmamk_f32 v95, v96, 0x3e38aa3b, v132
	v_fmamk_f32 v96, v97, 0x3e38aa3b, v132
	v_fmamk_f32 v97, v98, 0x3e38aa3b, v132
	v_fmamk_f32 v228, v68, 0x3e38aa3b, v132
	v_fmamk_f32 v229, v69, 0x3e38aa3b, v132
	v_fmamk_f32 v230, v70, 0x3e38aa3b, v132
	v_fmamk_f32 v231, v71, 0x3e38aa3b, v132
	v_fmamk_f32 v232, v72, 0x3e38aa3b, v132
	v_fmamk_f32 v233, v73, 0x3e38aa3b, v132
	v_fmamk_f32 v234, v74, 0x3e38aa3b, v132
	v_fmamk_f32 v235, v75, 0x3e38aa3b, v132
	v_fmamk_f32 v236, v76, 0x3e38aa3b, v132
	v_fmamk_f32 v237, v77, 0x3e38aa3b, v132
	v_fmamk_f32 v238, v78, 0x3e38aa3b, v132
	v_fmamk_f32 v239, v79, 0x3e38aa3b, v132
	v_fmamk_f32 v240, v80, 0x3e38aa3b, v132
	v_fmamk_f32 v241, v81, 0x3e38aa3b, v132
	v_exp_f32_e32 v125, v67
	s_waitcnt lgkmcnt(2)
	v_mov_b32_e32 v67, v66
	v_mov_b32_e32 v68, v66
	v_mov_b32_e32 v69, v66
	v_mov_b32_e32 v70, v66
	v_mov_b32_e32 v71, v66
	v_mov_b32_e32 v72, v66
	v_mov_b32_e32 v73, v66
	v_mov_b32_e32 v74, v66
	v_mov_b32_e32 v75, v66
	v_mov_b32_e32 v76, v66
	v_mov_b32_e32 v77, v66
	v_mov_b32_e32 v78, v66
	v_mov_b32_e32 v79, v66
	v_mov_b32_e32 v80, v66
	v_mov_b32_e32 v81, v66
	v_fmac_f32_e32 v132, 0x3e38aa3b, v83
	v_exp_f32_e32 v128, v84
	v_exp_f32_e32 v129, v85
	v_exp_f32_e32 v133, v86
	v_exp_f32_e32 v134, v87
	v_exp_f32_e32 v135, v88
	v_exp_f32_e32 v136, v89
	v_exp_f32_e32 v137, v90
	v_exp_f32_e32 v98, v91
	v_exp_f32_e32 v99, v92
	v_exp_f32_e32 v124, v93
	v_exp_f32_e32 v126, v94
	v_exp_f32_e32 v127, v95
	v_exp_f32_e32 v130, v96
	v_exp_f32_e32 v131, v97
	s_waitcnt lgkmcnt(1)
	v_mfma_f32_32x32x16_bf16 v[82:97], v[140:143], v[100:103], v[66:81]
	s_waitcnt lgkmcnt(0)
	v_mfma_f32_32x32x16_bf16 v[66:81], v[144:147], v[100:103], v[66:81]
	v_add_u32_e32 v144, v138, v212
	ds_read_b128 v[140:143], v144 offset:49152
	ds_read_b128 v[144:147], v144 offset:57344
	s_waitcnt lgkmcnt(1)
	v_mfma_f32_32x32x16_bf16 v[82:97], v[140:143], v[104:107], v[82:97]
	s_waitcnt lgkmcnt(0)
	v_mfma_f32_32x32x16_bf16 v[66:81], v[144:147], v[104:107], v[66:81]
	v_add_u32_e32 v144, v138, v213
	ds_read_b128 v[140:143], v144 offset:49152
	ds_read_b128 v[144:147], v144 offset:57344
	v_add_u32_e32 v138, v138, v214
	s_waitcnt lgkmcnt(1)
	v_mfma_f32_32x32x16_bf16 v[82:97], v[140:143], v[108:111], v[82:97]
	s_waitcnt lgkmcnt(0)
	v_mfma_f32_32x32x16_bf16 v[66:81], v[144:147], v[108:111], v[66:81]
	ds_read_b128 v[140:143], v138 offset:49152
	ds_read_b128 v[144:147], v138 offset:57344
	s_waitcnt lgkmcnt(1)
	v_mfma_f32_32x32x16_bf16 v[82:97], v[140:143], v[112:115], v[82:97]
	v_exp_f32_e32 v143, v231
	v_exp_f32_e32 v231, v237
	v_exp_f32_e32 v237, v132
	v_add_f32_e32 v132, 0, v125
	v_add_f32_e32 v132, v128, v132
	v_add_f32_e32 v132, v129, v132
	v_add_f32_e32 v132, v133, v132
	v_add_f32_e32 v132, v134, v132
	v_add_f32_e32 v132, v135, v132
	v_add_f32_e32 v132, v136, v132
	v_add_f32_e32 v132, v137, v132
	v_add_f32_e32 v132, v98, v132
	v_add_f32_e32 v132, v99, v132
	v_add_f32_e32 v132, v124, v132
	v_add_f32_e32 v132, v126, v132
	v_exp_f32_e32 v140, v228
	v_add_f32_e32 v132, v127, v132
	v_exp_f32_e32 v141, v229
	v_add_f32_e32 v132, v130, v132
	v_exp_f32_e32 v142, v230
	v_add_f32_e32 v132, v131, v132
	v_add_f32_e32 v132, v139, v132
	s_waitcnt lgkmcnt(0)
	v_mfma_f32_32x32x16_bf16 v[66:81], v[144:147], v[112:115], v[66:81]
	v_exp_f32_e32 v144, v232
	v_add_f32_e32 v132, v140, v132
	v_exp_f32_e32 v145, v233
	v_add_f32_e32 v132, v141, v132
	v_exp_f32_e32 v146, v234
	v_add_f32_e32 v132, v142, v132
	v_exp_f32_e32 v147, v235
	v_add_f32_e32 v132, v143, v132
	v_exp_f32_e32 v230, v236
	v_add_f32_e32 v132, v144, v132
	v_add_f32_e32 v132, v145, v132
	v_exp_f32_e32 v232, v238
	v_add_f32_e32 v132, v146, v132
	v_exp_f32_e32 v233, v239
	v_add_f32_e32 v132, v147, v132
	v_exp_f32_e32 v234, v240
	v_add_f32_e32 v132, v230, v132
	v_exp_f32_e32 v235, v241
	v_add_f32_e32 v132, v231, v132
	v_exp_f32_e32 v236, v242
	v_add_f32_e32 v132, v232, v132
	v_add_f32_e32 v132, v233, v132
	v_add_f32_e32 v132, v234, v132
	v_add_f32_e32 v132, v235, v132
	v_add_f32_e32 v132, v236, v132
	v_add_f32_e32 v228, v237, v132
	ds_bpermute_b32 v229, v187, v228
	v_cvt_pk_bf16_f32 v132, v125, v128
	v_cvt_pk_bf16_f32 v133, v129, v133
	v_cvt_pk_bf16_f32 v134, v134, v135
	v_cvt_pk_bf16_f32 v135, v136, v137
	v_cvt_pk_bf16_f32 v136, v98, v99
	v_cvt_pk_bf16_f32 v137, v124, v126
	v_cvt_pk_bf16_f32 v138, v127, v130
	v_cvt_pk_bf16_f32 v139, v131, v139
	v_cvt_pk_bf16_f32 v140, v140, v141
	v_cvt_pk_bf16_f32 v141, v142, v143
	v_cvt_pk_bf16_f32 v142, v144, v145
	v_cvt_pk_bf16_f32 v143, v146, v147
	v_cvt_pk_bf16_f32 v144, v230, v231
	v_cvt_pk_bf16_f32 v145, v232, v233
	v_cvt_pk_bf16_f32 v146, v234, v235
	v_cvt_pk_bf16_f32 v147, v236, v237
	s_nop 0
	v_permlane32_swap_b32_e32 v132, v134
	v_permlane32_swap_b32_e32 v133, v135
	v_permlane32_swap_b32_e32 v136, v138
	v_permlane32_swap_b32_e32 v137, v139
	v_permlane32_swap_b32_e32 v140, v142
	v_permlane32_swap_b32_e32 v141, v143
	v_permlane32_swap_b32_e32 v144, v146
	v_permlane32_swap_b32_e32 v145, v147
	s_waitcnt vmcnt(2)
	s_barrier
	s_setprio 0
	s_lshl_b32 s45, s39, 14
	s_add_i32 s45, s45, s44
	s_mov_b32 m0, s45
	s_add_i32 s45, s45, 0x2000
	global_load_lds_dwordx4 v[120:121], off
	s_mov_b32 m0, s45
	v_lshl_add_u64 v[120:121], v[120:121], 0, s[62:63]
	global_load_lds_dwordx4 v[122:123], off
	v_lshl_add_u64 v[122:123], v[122:123], 0, s[62:63]
	v_add_u32_e32 v98, s43, v188
	ds_read_b64_tr_b16 v[230:231], v98 offset:0
	ds_read_b64_tr_b16 v[232:233], v98 offset:0x800
	ds_read_b64_tr_b16 v[234:235], v98 offset:0x1000
	ds_read_b64_tr_b16 v[236:237], v98 offset:0x1800
	ds_read_b64_tr_b16 v[238:239], v98 offset:0x2000
	ds_read_b64_tr_b16 v[240:241], v98 offset:0x2800
	ds_read_b64_tr_b16 v[242:243], v98 offset:0x3000
	ds_read_b64_tr_b16 v[244:245], v98 offset:0x3800
	s_waitcnt lgkmcnt(0)
	s_nop 0
	v_mfma_f32_32x32x16_bf16 v[50:65], v[132:135], v[230:233], v[50:65]
	ds_read_b64_tr_b16 v[230:231], v98 offset:0x200
	ds_read_b64_tr_b16 v[232:233], v98 offset:0xa00
	v_mfma_f32_32x32x16_bf16 v[50:65], v[136:139], v[234:237], v[50:65]
	ds_read_b64_tr_b16 v[234:235], v98 offset:0x1200
	ds_read_b64_tr_b16 v[236:237], v98 offset:0x1a00
	v_mfma_f32_32x32x16_bf16 v[50:65], v[140:143], v[238:241], v[50:65]
	ds_read_b64_tr_b16 v[238:239], v98 offset:0x2200
	ds_read_b64_tr_b16 v[240:241], v98 offset:0x2a00
	v_mfma_f32_32x32x16_bf16 v[50:65], v[144:147], v[242:245], v[50:65]
	ds_read_b64_tr_b16 v[242:243], v98 offset:0x3200
	ds_read_b64_tr_b16 v[244:245], v98 offset:0x3a00
	s_waitcnt lgkmcnt(0)
	v_mfma_f32_32x32x16_bf16 v[34:49], v[132:135], v[230:233], v[34:49]
	ds_read_b64_tr_b16 v[230:231], v98 offset:0x400
	ds_read_b64_tr_b16 v[232:233], v98 offset:0xc00
	v_mfma_f32_32x32x16_bf16 v[34:49], v[136:139], v[234:237], v[34:49]
	ds_read_b64_tr_b16 v[234:235], v98 offset:0x1400
	ds_read_b64_tr_b16 v[236:237], v98 offset:0x1c00
	v_mfma_f32_32x32x16_bf16 v[34:49], v[140:143], v[238:241], v[34:49]
	ds_read_b64_tr_b16 v[238:239], v98 offset:0x2400
	ds_read_b64_tr_b16 v[240:241], v98 offset:0x2c00
	v_mfma_f32_32x32x16_bf16 v[34:49], v[144:147], v[242:245], v[34:49]
	ds_read_b64_tr_b16 v[242:243], v98 offset:0x3400
	ds_read_b64_tr_b16 v[244:245], v98 offset:0x3c00
	s_waitcnt lgkmcnt(0)
	v_mfma_f32_32x32x16_bf16 v[18:33], v[132:135], v[230:233], v[18:33]
	ds_read_b64_tr_b16 v[230:231], v98 offset:0x600
	ds_read_b64_tr_b16 v[232:233], v98 offset:0xe00
	v_mfma_f32_32x32x16_bf16 v[18:33], v[136:139], v[234:237], v[18:33]
	ds_read_b64_tr_b16 v[234:235], v98 offset:0x1600
	ds_read_b64_tr_b16 v[236:237], v98 offset:0x1e00
	v_mfma_f32_32x32x16_bf16 v[18:33], v[140:143], v[238:241], v[18:33]
	ds_read_b64_tr_b16 v[238:239], v98 offset:0x2600
	ds_read_b64_tr_b16 v[240:241], v98 offset:0x2e00
	v_mfma_f32_32x32x16_bf16 v[18:33], v[144:147], v[242:245], v[18:33]
	ds_read_b64_tr_b16 v[242:243], v98 offset:0x3600
	ds_read_b64_tr_b16 v[244:245], v98 offset:0x3e00
	s_waitcnt lgkmcnt(0)
	v_mfma_f32_32x32x16_bf16 v[2:17], v[132:135], v[230:233], v[2:17]
	v_mfma_f32_32x32x16_bf16 v[2:17], v[136:139], v[234:237], v[2:17]
	v_mfma_f32_32x32x16_bf16 v[2:17], v[140:143], v[238:241], v[2:17]
	v_mfma_f32_32x32x16_bf16 v[2:17], v[144:147], v[242:245], v[2:17]
	s_and_saveexec_b64 s[4:5], vcc
	s_cbranch_execz .LBB0_254
	flat_load_dwordx4 v[132:135], v[182:183] offset:512
	flat_load_dwordx4 v[136:139], v[182:183] offset:640
	flat_load_dwordx4 v[140:143], v[182:183] offset:544
	flat_load_dwordx4 v[144:147], v[182:183] offset:672
	flat_load_dwordx4 v[230:233], v[182:183] offset:576
	flat_load_dwordx4 v[234:237], v[182:183] offset:704
	flat_load_dwordx4 v[238:241], v[182:183] offset:608
	flat_load_dwordx4 v[242:245], v[182:183] offset:736
	s_waitcnt vmcnt(0) lgkmcnt(0)
	v_sub_u32_e32 v98, v132, v167
	v_sub_u32_e32 v132, v133, v167
	v_sub_u32_e32 v133, v137, v167
	v_sub_u32_e32 v137, v139, v167
	v_sub_u32_e32 v139, v144, v167
	v_sub_u32_e32 v144, v146, v167
	v_sub_u32_e32 v146, v230, v167
	v_sub_u32_e32 v230, v231, v167
	v_sub_u32_e32 v99, v136, v167
	v_sub_u32_e32 v134, v134, v167
	v_sub_u32_e32 v136, v138, v167
	v_sub_u32_e32 v135, v135, v167
	v_sub_u32_e32 v138, v140, v167
	v_sub_u32_e32 v140, v141, v167
	v_sub_u32_e32 v141, v145, v167
	v_sub_u32_e32 v142, v142, v167
	v_sub_u32_e32 v143, v143, v167
	v_sub_u32_e32 v145, v147, v167
	v_med3_i32 v230, v230, s87, v197
	v_med3_i32 v98, v98, s87, v197
	v_med3_i32 v99, v99, s87, v197
	v_med3_i32 v132, v132, s87, v197
	v_med3_i32 v133, v133, s87, v197
	v_med3_i32 v134, v134, s87, v197
	v_med3_i32 v136, v136, s87, v197
	v_med3_i32 v135, v135, s87, v197
	v_med3_i32 v137, v137, s87, v197
	v_med3_i32 v138, v138, s87, v197
	v_med3_i32 v139, v139, s87, v197
	v_med3_i32 v140, v140, s87, v197
	v_med3_i32 v141, v141, s87, v197
	v_med3_i32 v142, v142, s87, v197
	v_med3_i32 v144, v144, s87, v197
	v_med3_i32 v143, v143, s87, v197
	v_med3_i32 v145, v145, s87, v197
	v_lshl_add_u32 v246, v230, 2, s86
	v_sub_u32_e32 v230, v232, v167
	v_sub_u32_e32 v232, v236, v167
	v_sub_u32_e32 v147, v234, v167
	v_sub_u32_e32 v231, v235, v167
	v_lshl_add_u32 v98, v98, 2, s86
	v_lshl_add_u32 v99, v99, 2, s86
	v_lshl_add_u32 v234, v132, 2, s86
	v_lshl_add_u32 v133, v133, 2, s86
	v_lshl_add_u32 v134, v134, 2, s86
	v_lshl_add_u32 v136, v136, 2, s86
	v_lshl_add_u32 v135, v135, 2, s86
	v_lshl_add_u32 v137, v137, 2, s86
	v_lshl_add_u32 v138, v138, 2, s86
	v_lshl_add_u32 v139, v139, 2, s86
	v_lshl_add_u32 v235, v140, 2, s86
	v_lshl_add_u32 v141, v141, 2, s86
	v_lshl_add_u32 v142, v142, 2, s86
	v_lshl_add_u32 v144, v144, 2, s86
	v_lshl_add_u32 v143, v143, 2, s86
	v_lshl_add_u32 v145, v145, 2, s86
	v_med3_i32 v230, v230, s87, v197
	v_med3_i32 v232, v232, s87, v197
	ds_read_b32 v98, v98 offset:1220
	ds_read_b32 v132, v99 offset:1220
	ds_read_b32 v99, v234 offset:1220
	ds_read_b32 v133, v133 offset:1220
	ds_read_b32 v134, v134 offset:1220
	ds_read_b32 v136, v136 offset:1220
	ds_read_b32 v135, v135 offset:1220
	ds_read_b32 v137, v137 offset:1220
	ds_read_b32 v138, v138 offset:1220
	ds_read_b32 v140, v139 offset:1220
	ds_read_b32 v139, v235 offset:1220
	ds_read_b32 v141, v141 offset:1220
	ds_read_b32 v142, v142 offset:1220
	ds_read_b32 v144, v144 offset:1220
	ds_read_b32 v143, v143 offset:1220
	ds_read_b32 v145, v145 offset:1220
	v_lshl_add_u32 v234, v230, 2, s86
	v_lshl_add_u32 v235, v232, 2, s86
	v_sub_u32_e32 v230, v233, v167
	v_sub_u32_e32 v232, v237, v167
	v_med3_i32 v146, v146, s87, v197
	v_med3_i32 v147, v147, s87, v197
	v_med3_i32 v231, v231, s87, v197
	v_med3_i32 v230, v230, s87, v197
	v_med3_i32 v232, v232, s87, v197
	v_lshl_add_u32 v146, v146, 2, s86
	v_lshl_add_u32 v147, v147, 2, s86
	v_lshl_add_u32 v231, v231, 2, s86
	v_lshl_add_u32 v233, v230, 2, s86
	v_lshl_add_u32 v236, v232, 2, s86
	ds_read_b32 v146, v146 offset:1220
	ds_read_b32 v230, v147 offset:1220
	ds_read_b32 v147, v246 offset:1220
	ds_read_b32 v231, v231 offset:1220
	ds_read_b32 v232, v234 offset:1220
	ds_read_b32 v234, v235 offset:1220
	ds_read_b32 v233, v233 offset:1220
	ds_read_b32 v235, v236 offset:1220
	v_sub_u32_e32 v236, v238, v167
	v_sub_u32_e32 v238, v239, v167
	v_med3_i32 v238, v238, s87, v197
	v_sub_u32_e32 v237, v242, v167
	v_lshl_add_u32 v242, v238, 2, s86
	v_sub_u32_e32 v238, v240, v167
	v_med3_i32 v238, v238, s87, v197
	v_sub_u32_e32 v240, v244, v167
	v_sub_u32_e32 v239, v243, v167
	v_med3_i32 v240, v240, s87, v197
	v_lshl_add_u32 v243, v238, 2, s86
	v_sub_u32_e32 v238, v241, v167
	v_med3_i32 v236, v236, s87, v197
	v_med3_i32 v237, v237, s87, v197
	v_med3_i32 v239, v239, s87, v197
	v_lshl_add_u32 v244, v240, 2, s86
	v_med3_i32 v238, v238, s87, v197
	v_sub_u32_e32 v240, v245, v167
	v_lshl_add_u32 v236, v236, 2, s86
	v_lshl_add_u32 v237, v237, 2, s86
	v_lshl_add_u32 v239, v239, 2, s86
	v_med3_i32 v240, v240, s87, v197
	v_lshl_add_u32 v241, v238, 2, s86
	v_lshl_add_u32 v245, v240, 2, s86
	ds_read_b32 v236, v236 offset:1220
	ds_read_b32 v238, v237 offset:1220
	ds_read_b32 v240, v243 offset:1220
	ds_read_b32 v241, v241 offset:1220
	ds_read_b32 v237, v242 offset:1220
	ds_read_b32 v243, v245 offset:1220
	ds_read_b32 v242, v244 offset:1220
	ds_read_b32 v239, v239 offset:1220
	s_waitcnt lgkmcnt(4)
	v_pk_add_f32 v[96:97], v[96:97], v[240:241]
	s_waitcnt lgkmcnt(3)
	v_pk_add_f32 v[94:95], v[94:95], v[236:237]
	v_pk_add_f32 v[92:93], v[92:93], v[232:233]
	v_pk_add_f32 v[90:91], v[90:91], v[146:147]
	v_pk_add_f32 v[88:89], v[88:89], v[142:143]
	v_pk_add_f32 v[86:87], v[86:87], v[138:139]
	v_pk_add_f32 v[84:85], v[84:85], v[134:135]
	v_pk_add_f32 v[82:83], v[82:83], v[98:99]
	s_waitcnt lgkmcnt(1)
	v_pk_add_f32 v[80:81], v[80:81], v[242:243]
	s_waitcnt lgkmcnt(0)
	v_pk_add_f32 v[78:79], v[78:79], v[238:239]
	v_pk_add_f32 v[76:77], v[76:77], v[234:235]
	v_pk_add_f32 v[74:75], v[74:75], v[230:231]
	v_pk_add_f32 v[72:73], v[72:73], v[144:145]
	v_pk_add_f32 v[70:71], v[70:71], v[140:141]
	v_pk_add_f32 v[68:69], v[68:69], v[136:137]
	v_pk_add_f32 v[66:67], v[66:67], v[132:133]

.LskewA_out:
	s_setprio 0
	v_lshl_add_u64 v[66:67], s[20:21], 2, v[176:177]
	flat_load_dword v66, v[66:67]
	s_waitcnt vmcnt(0) lgkmcnt(0)
	s_barrier
	v_sub_u32_e32 v66, v66, v201
	v_cmp_lt_i32_e32 vcc, s87, v66
	v_cmp_gt_i32_e64 s[12:13], s84, v66
	v_mov_b32_e32 v66, 0
	s_and_saveexec_b64 s[4:5], s[12:13]
	v_mov_b32_e32 v66, s86
	ds_read_b32 v66, v66
	s_or_b64 exec, exec, s[4:5]
	v_add_u32_e32 v98, s14, v211
	v_add_u32_e32 v82, v98, v210
	ds_read_b128 v[178:181], v82 offset:49152
	ds_read_b128 v[182:185], v82 offset:57344
	s_waitcnt lgkmcnt(2)
	v_mov_b32_e32 v67, v66
	v_mov_b32_e32 v68, v66
	v_mov_b32_e32 v69, v66
	v_mov_b32_e32 v70, v66
	v_mov_b32_e32 v71, v66
	v_mov_b32_e32 v72, v66
	v_mov_b32_e32 v73, v66
	v_mov_b32_e32 v74, v66
	v_mov_b32_e32 v75, v66
	v_mov_b32_e32 v76, v66
	v_mov_b32_e32 v77, v66
	v_mov_b32_e32 v78, v66
	v_mov_b32_e32 v79, v66
	v_mov_b32_e32 v80, v66
	v_mov_b32_e32 v81, v66
	v_exp_f32_e32 v138, v138
	v_exp_f32_e32 v139, v139
	s_waitcnt lgkmcnt(1)
	v_mfma_f32_32x32x16_bf16 v[82:97], v[178:181], v[100:103], v[66:81]
	v_exp_f32_e32 v136, v136
	v_exp_f32_e32 v137, v137
	v_exp_f32_e32 v221, v126
	v_exp_f32_e32 v222, v127
	v_exp_f32_e32 v223, v124
	v_exp_f32_e32 v125, v125
	s_waitcnt lgkmcnt(0)
	v_mfma_f32_32x32x16_bf16 v[66:81], v[182:185], v[100:103], v[66:81]
	v_add_u32_e32 v182, v98, v212
	ds_read_b128 v[178:181], v182 offset:49152
	ds_read_b128 v[182:185], v182 offset:57344
	s_waitcnt lgkmcnt(1)
	v_mfma_f32_32x32x16_bf16 v[82:97], v[178:181], v[104:107], v[82:97]
	s_waitcnt lgkmcnt(0)
	v_mfma_f32_32x32x16_bf16 v[66:81], v[182:185], v[104:107], v[66:81]
	v_add_u32_e32 v182, v98, v213
	ds_read_b128 v[178:181], v182 offset:49152
	ds_read_b128 v[182:185], v182 offset:57344
	v_add_u32_e32 v98, v98, v214
	s_waitcnt lgkmcnt(1)
	v_mfma_f32_32x32x16_bf16 v[82:97], v[178:181], v[108:111], v[82:97]
	s_waitcnt lgkmcnt(0)
	v_mfma_f32_32x32x16_bf16 v[66:81], v[182:185], v[108:111], v[66:81]
	ds_read_b128 v[178:181], v98 offset:49152
	ds_read_b128 v[182:185], v98 offset:57344
	v_add_f32_e32 v98, 0, v230
	v_add_f32_e32 v98, v234, v98
	v_add_f32_e32 v98, v231, v98
	v_add_f32_e32 v98, v235, v98
	v_add_f32_e32 v98, v232, v98
	v_add_f32_e32 v98, v236, v98
	v_add_f32_e32 v98, v233, v98
	v_add_f32_e32 v98, v237, v98
	v_add_f32_e32 v98, v140, v98
	v_add_f32_e32 v98, v143, v98
	v_add_f32_e32 v98, v141, v98
	v_add_f32_e32 v98, v144, v98
	v_add_f32_e32 v98, v142, v98
	v_add_f32_e32 v98, v146, v98
	v_add_f32_e32 v98, v145, v98
	v_add_f32_e32 v98, v147, v98
	s_waitcnt lgkmcnt(1)
	v_mfma_f32_32x32x16_bf16 v[82:97], v[178:181], v[112:115], v[82:97]
	v_exp_f32_e32 v178, v134
	v_add_f32_e32 v98, v138, v98
	v_exp_f32_e32 v179, v135
	v_add_f32_e32 v98, v139, v98
	v_exp_f32_e32 v180, v132
	v_add_f32_e32 v98, v136, v98
	v_exp_f32_e32 v181, v133
	v_add_f32_e32 v98, v137, v98
	s_waitcnt lgkmcnt(0)
	v_mfma_f32_32x32x16_bf16 v[66:81], v[182:185], v[112:115], v[66:81]
	v_exp_f32_e32 v182, v130
	v_add_f32_e32 v98, v178, v98
	v_exp_f32_e32 v183, v131
	v_add_f32_e32 v98, v179, v98
	v_exp_f32_e32 v184, v128
	v_add_f32_e32 v98, v180, v98
	v_exp_f32_e32 v185, v129
	v_add_f32_e32 v98, v181, v98
	v_add_f32_e32 v98, v182, v98
	v_add_f32_e32 v98, v183, v98
	v_add_f32_e32 v98, v184, v98
	v_add_f32_e32 v98, v185, v98
	v_add_f32_e32 v98, v221, v98
	v_add_f32_e32 v98, v222, v98
	v_add_f32_e32 v98, v223, v98
	v_add_f32_e32 v98, v125, v98
	ds_bpermute_b32 v124, v187, v98
	v_cvt_pk_bf16_f32 v126, v230, v234
	v_cvt_pk_bf16_f32 v127, v231, v235
	v_cvt_pk_bf16_f32 v128, v232, v236
	v_cvt_pk_bf16_f32 v129, v233, v237
	v_cvt_pk_bf16_f32 v130, v140, v143
	v_cvt_pk_bf16_f32 v131, v141, v144
	v_cvt_pk_bf16_f32 v132, v142, v146
	v_cvt_pk_bf16_f32 v133, v145, v147
	v_cvt_pk_bf16_f32 v134, v138, v139
	v_cvt_pk_bf16_f32 v135, v136, v137
	v_cvt_pk_bf16_f32 v136, v178, v179
	v_cvt_pk_bf16_f32 v137, v180, v181
	v_cvt_pk_bf16_f32 v138, v182, v183
	v_cvt_pk_bf16_f32 v139, v184, v185
	v_cvt_pk_bf16_f32 v140, v221, v222
	v_cvt_pk_bf16_f32 v141, v223, v125
	s_nop 0
	v_permlane32_swap_b32_e32 v126, v128
	v_permlane32_swap_b32_e32 v127, v129
	v_permlane32_swap_b32_e32 v130, v132
	v_permlane32_swap_b32_e32 v131, v133
	v_permlane32_swap_b32_e32 v134, v136
	v_permlane32_swap_b32_e32 v135, v137
	v_permlane32_swap_b32_e32 v138, v140
	v_permlane32_swap_b32_e32 v139, v141
	v_add_u32_e32 v125, s41, v188
	ds_read_b64_tr_b16 v[142:143], v125 offset:0
	ds_read_b64_tr_b16 v[144:145], v125 offset:0x800
	ds_read_b64_tr_b16 v[178:179], v125 offset:0x1000
	ds_read_b64_tr_b16 v[180:181], v125 offset:0x1800
	ds_read_b64_tr_b16 v[182:183], v125 offset:0x2000
	ds_read_b64_tr_b16 v[184:185], v125 offset:0x2800
	ds_read_b64_tr_b16 v[226:227], v125 offset:0x3000
	ds_read_b64_tr_b16 v[228:229], v125 offset:0x3800
	s_waitcnt lgkmcnt(0)
	s_nop 0
	v_mfma_f32_32x32x16_bf16 v[50:65], v[126:129], v[142:145], v[50:65]
	ds_read_b64_tr_b16 v[142:143], v125 offset:0x200
	ds_read_b64_tr_b16 v[144:145], v125 offset:0xa00
	v_mfma_f32_32x32x16_bf16 v[50:65], v[130:133], v[178:181], v[50:65]
	ds_read_b64_tr_b16 v[178:179], v125 offset:0x1200
	ds_read_b64_tr_b16 v[180:181], v125 offset:0x1a00
	v_mfma_f32_32x32x16_bf16 v[50:65], v[134:137], v[182:185], v[50:65]
	ds_read_b64_tr_b16 v[182:183], v125 offset:0x2200
	ds_read_b64_tr_b16 v[184:185], v125 offset:0x2a00
	v_mfma_f32_32x32x16_bf16 v[50:65], v[138:141], v[226:229], v[50:65]
	ds_read_b64_tr_b16 v[226:227], v125 offset:0x3200
	ds_read_b64_tr_b16 v[228:229], v125 offset:0x3a00
	s_waitcnt lgkmcnt(0)
	v_mfma_f32_32x32x16_bf16 v[34:49], v[126:129], v[142:145], v[34:49]
	ds_read_b64_tr_b16 v[142:143], v125 offset:0x400
	ds_read_b64_tr_b16 v[144:145], v125 offset:0xc00
	v_mfma_f32_32x32x16_bf16 v[34:49], v[130:133], v[178:181], v[34:49]
	ds_read_b64_tr_b16 v[178:179], v125 offset:0x1400
	ds_read_b64_tr_b16 v[180:181], v125 offset:0x1c00
	v_mfma_f32_32x32x16_bf16 v[34:49], v[134:137], v[182:185], v[34:49]
	ds_read_b64_tr_b16 v[182:183], v125 offset:0x2400
	ds_read_b64_tr_b16 v[184:185], v125 offset:0x2c00
	v_mfma_f32_32x32x16_bf16 v[34:49], v[138:141], v[226:229], v[34:49]
	ds_read_b64_tr_b16 v[226:227], v125 offset:0x3400
	ds_read_b64_tr_b16 v[228:229], v125 offset:0x3c00
	s_waitcnt lgkmcnt(0)
	v_mfma_f32_32x32x16_bf16 v[18:33], v[126:129], v[142:145], v[18:33]
	ds_read_b64_tr_b16 v[142:143], v125 offset:0x600
	ds_read_b64_tr_b16 v[144:145], v125 offset:0xe00
	v_mfma_f32_32x32x16_bf16 v[18:33], v[130:133], v[178:181], v[18:33]
	ds_read_b64_tr_b16 v[178:179], v125 offset:0x1600
	ds_read_b64_tr_b16 v[180:181], v125 offset:0x1e00
	v_mfma_f32_32x32x16_bf16 v[18:33], v[134:137], v[182:185], v[18:33]
	ds_read_b64_tr_b16 v[182:183], v125 offset:0x2600
	ds_read_b64_tr_b16 v[184:185], v125 offset:0x2e00
	v_mfma_f32_32x32x16_bf16 v[18:33], v[138:141], v[226:229], v[18:33]
	ds_read_b64_tr_b16 v[226:227], v125 offset:0x3600
	ds_read_b64_tr_b16 v[228:229], v125 offset:0x3e00
	s_waitcnt lgkmcnt(0)
	v_mfma_f32_32x32x16_bf16 v[2:17], v[126:129], v[142:145], v[2:17]
	v_mfma_f32_32x32x16_bf16 v[2:17], v[130:133], v[178:181], v[2:17]
	v_mfma_f32_32x32x16_bf16 v[2:17], v[134:137], v[182:185], v[2:17]
	v_mfma_f32_32x32x16_bf16 v[2:17], v[138:141], v[226:229], v[2:17]
	s_and_saveexec_b64 s[4:5], vcc
	s_cbranch_execz .LBB0_266
	v_lshl_add_u64 v[126:127], s[22:23], 2, v[168:169]
	v_lshlrev_b32_e32 v128, 2, v0
	v_mov_b32_e32 v129, v1
	v_lshl_add_u64 v[146:147], v[126:127], 0, v[128:129]
	flat_load_dwordx4 v[126:129], v[146:147]
	flat_load_dwordx4 v[130:133], v[146:147] offset:128
	flat_load_dwordx4 v[134:137], v[146:147] offset:32
	flat_load_dwordx4 v[138:141], v[146:147] offset:160
	flat_load_dwordx4 v[142:145], v[146:147] offset:64
	flat_load_dwordx4 v[178:181], v[146:147] offset:192
	flat_load_dwordx4 v[182:185], v[146:147] offset:96
	flat_load_dwordx4 v[226:229], v[146:147] offset:224
	s_waitcnt vmcnt(0) lgkmcnt(0)
	v_sub_u32_e32 v125, v126, v167
	v_sub_u32_e32 v126, v130, v167
	v_sub_u32_e32 v127, v127, v167
	v_sub_u32_e32 v130, v131, v167
	v_sub_u32_e32 v131, v132, v167
	v_sub_u32_e32 v132, v133, v167
	v_sub_u32_e32 v133, v134, v167
	v_sub_u32_e32 v134, v138, v167
	v_sub_u32_e32 v135, v135, v167
	v_sub_u32_e32 v138, v139, v167
	v_sub_u32_e32 v139, v140, v167
	v_sub_u32_e32 v128, v128, v167
	v_sub_u32_e32 v129, v129, v167
	v_sub_u32_e32 v136, v136, v167
	v_sub_u32_e32 v137, v137, v167
	v_sub_u32_e32 v140, v141, v167
	v_sub_u32_e32 v141, v142, v167
	v_sub_u32_e32 v142, v178, v167
	v_sub_u32_e32 v143, v143, v167
	v_med3_i32 v125, v125, s87, v197
	v_med3_i32 v127, v127, s87, v197
	v_med3_i32 v130, v130, s87, v197
	v_med3_i32 v131, v131, s87, v197
	v_med3_i32 v135, v135, s87, v197
	v_med3_i32 v138, v138, s87, v197
	v_med3_i32 v139, v139, s87, v197
	v_med3_i32 v126, v126, s87, v197
	v_med3_i32 v128, v128, s87, v197
	v_med3_i32 v129, v129, s87, v197
	v_med3_i32 v132, v132, s87, v197
	v_med3_i32 v133, v133, s87, v197
	v_med3_i32 v134, v134, s87, v197
	v_med3_i32 v136, v136, s87, v197
	v_med3_i32 v137, v137, s87, v197
	v_med3_i32 v140, v140, s87, v197
	v_med3_i32 v141, v141, s87, v197
	v_med3_i32 v142, v142, s87, v197
	v_med3_i32 v143, v143, s87, v197
	v_lshl_add_u32 v125, v125, 2, s86
	v_lshl_add_u32 v127, v127, 2, s86
	v_lshl_add_u32 v130, v130, 2, s86
	v_lshl_add_u32 v131, v131, 2, s86
	v_lshl_add_u32 v135, v135, 2, s86
	v_lshl_add_u32 v138, v138, 2, s86
	v_lshl_add_u32 v139, v139, 2, s86
	v_sub_u32_e32 v146, v179, v167
	v_lshl_add_u32 v147, v126, 2, s86
	v_lshl_add_u32 v178, v128, 2, s86
	v_lshl_add_u32 v179, v129, 2, s86
	v_lshl_add_u32 v221, v132, 2, s86
	v_lshl_add_u32 v222, v133, 2, s86
	v_lshl_add_u32 v223, v134, 2, s86
	v_lshl_add_u32 v225, v136, 2, s86
	v_lshl_add_u32 v230, v137, 2, s86
	v_lshl_add_u32 v231, v140, 2, s86
	v_lshl_add_u32 v232, v141, 2, s86
	v_lshl_add_u32 v233, v142, 2, s86
	ds_read_b32 v126, v125 offset:1220
	ds_read_b32 v128, v147 offset:1220
	ds_read_b32 v127, v127 offset:1220
	ds_read_b32 v129, v130 offset:1220
	ds_read_b32 v130, v178 offset:1220
	ds_read_b32 v132, v131 offset:1220
	ds_read_b32 v131, v179 offset:1220
	ds_read_b32 v133, v221 offset:1220
	ds_read_b32 v134, v222 offset:1220
	ds_read_b32 v136, v223 offset:1220
	ds_read_b32 v135, v135 offset:1220
	ds_read_b32 v137, v138 offset:1220
	ds_read_b32 v138, v225 offset:1220
	ds_read_b32 v140, v139 offset:1220
	ds_read_b32 v139, v230 offset:1220
	ds_read_b32 v141, v231 offset:1220
	v_lshl_add_u32 v125, v143, 2, s86
	v_sub_u32_e32 v142, v144, v167
	v_sub_u32_e32 v143, v180, v167
	v_med3_i32 v142, v142, s87, v197
	v_med3_i32 v143, v143, s87, v197
	v_lshl_add_u32 v147, v142, 2, s86
	v_lshl_add_u32 v178, v143, 2, s86
	v_sub_u32_e32 v142, v145, v167
	v_sub_u32_e32 v143, v181, v167
	v_med3_i32 v146, v146, s87, v197
	v_med3_i32 v142, v142, s87, v197
	v_med3_i32 v143, v143, s87, v197
	v_lshl_add_u32 v146, v146, 2, s86
	v_lshl_add_u32 v179, v142, 2, s86
	v_lshl_add_u32 v180, v143, 2, s86
	ds_read_b32 v142, v232 offset:1220
	ds_read_b32 v144, v233 offset:1220
	ds_read_b32 v143, v125 offset:1220
	ds_read_b32 v145, v146 offset:1220
	ds_read_b32 v146, v147 offset:1220
	ds_read_b32 v178, v178 offset:1220
	ds_read_b32 v147, v179 offset:1220
	ds_read_b32 v179, v180 offset:1220
	v_sub_u32_e32 v180, v226, v167
	v_med3_i32 v180, v180, s87, v197
	v_sub_u32_e32 v125, v182, v167
	v_lshl_add_u32 v181, v180, 2, s86
	v_sub_u32_e32 v180, v183, v167
	v_sub_u32_e32 v182, v227, v167
	v_med3_i32 v180, v180, s87, v197
	v_med3_i32 v182, v182, s87, v197
	v_lshl_add_u32 v183, v180, 2, s86
	v_lshl_add_u32 v221, v182, 2, s86
	v_sub_u32_e32 v180, v184, v167
	v_sub_u32_e32 v182, v228, v167
	v_med3_i32 v180, v180, s87, v197
	v_med3_i32 v182, v182, s87, v197
	v_lshl_add_u32 v184, v180, 2, s86
	v_lshl_add_u32 v222, v182, 2, s86
	v_sub_u32_e32 v180, v185, v167
	v_sub_u32_e32 v182, v229, v167
	v_med3_i32 v125, v125, s87, v197
	v_med3_i32 v180, v180, s87, v197
	v_med3_i32 v182, v182, s87, v197
	v_lshl_add_u32 v125, v125, 2, s86
	v_lshl_add_u32 v185, v180, 2, s86
	v_lshl_add_u32 v223, v182, 2, s86
	ds_read_b32 v180, v125 offset:1220
	ds_read_b32 v182, v181 offset:1220
	ds_read_b32 v184, v184 offset:1220
	ds_read_b32 v185, v185 offset:1220
	ds_read_b32 v181, v183 offset:1220
	ds_read_b32 v223, v223 offset:1220
	ds_read_b32 v222, v222 offset:1220
	ds_read_b32 v183, v221 offset:1220
	s_waitcnt lgkmcnt(4)
	v_pk_add_f32 v[96:97], v[96:97], v[184:185]
	s_waitcnt lgkmcnt(3)
	v_pk_add_f32 v[94:95], v[94:95], v[180:181]
	v_pk_add_f32 v[92:93], v[92:93], v[146:147]
	v_pk_add_f32 v[90:91], v[90:91], v[142:143]
	v_pk_add_f32 v[88:89], v[88:89], v[138:139]
	v_pk_add_f32 v[86:87], v[86:87], v[134:135]
	v_pk_add_f32 v[84:85], v[84:85], v[130:131]
	v_pk_add_f32 v[82:83], v[82:83], v[126:127]
	s_waitcnt lgkmcnt(1)
	v_pk_add_f32 v[80:81], v[80:81], v[222:223]
	s_waitcnt lgkmcnt(0)
	v_pk_add_f32 v[78:79], v[78:79], v[182:183]
	v_pk_add_f32 v[76:77], v[76:77], v[178:179]
	v_pk_add_f32 v[74:75], v[74:75], v[144:145]
	v_pk_add_f32 v[72:73], v[72:73], v[140:141]
	v_pk_add_f32 v[70:71], v[70:71], v[136:137]
	v_pk_add_f32 v[68:69], v[68:69], v[132:133]
	v_pk_add_f32 v[66:67], v[66:67], v[128:129]
